# removed 212 redundant s_nop 0 between top-k cmp/addc asm blocks
# speedup vs baseline: 1.0024x; 1.0024x over previous
;     ...
;     unsigned T = 0u;
; #pragma unroll 1
;     ...
;         const unsigned cand = T | (1u << bit);
;         unsigned c0 = 0u;
; #pragma unroll
;         for (int j = 0; j < NJ; ++j) asm("v_cmp_ge_u32_e32 vcc, %1, %2\n\tv_addc_co_u32_e32 %0, vcc, 0, %0, vcc" : "+v"(c0) : "v"(key[j]), "v"(cand) : "vcc");
;         const int cnt = wave_count6(c0);
;         if (cnt >= 256) T = cand;
;         if (cnt == 256) break;
;     }
;     unsigned cg = 0u, ce = 0u;
; #pragma unroll
;     for (int j = 0; j < NJ; ++j) { asm("v_cmp_gt_u32_e32 vcc, %1, %2\n\tv_addc_co_u32_e32 %0, vcc, 0, %0, vcc" : "+v"(cg) : "v"(key[j]), "v"(T) : "vcc");
;                                    asm("v_cmp_eq_u32_e32 vcc, %1, %2\n\tv_addc_co_u32_e32 %0, vcc, 0, %0, vcc" : "+v"(ce) : "v"(key[j]), "v"(T) : "vcc"); }
;     const int gt = wave_count6(cg), eq = wave_count6(ce);
;     const int need = 256 - gt; int lim = SEQ;
.LBB0_449:
	v_lshlrev_b32_e64 v58, v57, 1
	v_mov_b32_e32 v59, 0
	v_or_b32_e32 v58, v58, v56
	v_cmp_ge_u32_e32 vcc, v1, v58
	v_addc_co_u32_e32 v59, vcc, 0, v59, vcc
	v_cmp_ge_u32_e32 vcc, v0, v58
	v_addc_co_u32_e32 v59, vcc, 0, v59, vcc
	v_cmp_ge_u32_e32 vcc, v3, v58
	v_addc_co_u32_e32 v59, vcc, 0, v59, vcc
	v_cmp_ge_u32_e32 vcc, v2, v58
	v_addc_co_u32_e32 v59, vcc, 0, v59, vcc
	v_cmp_ge_u32_e32 vcc, v5, v58
	v_addc_co_u32_e32 v59, vcc, 0, v59, vcc
	v_cmp_ge_u32_e32 vcc, v4, v58
	v_addc_co_u32_e32 v59, vcc, 0, v59, vcc
	v_cmp_ge_u32_e32 vcc, v7, v58
	v_addc_co_u32_e32 v59, vcc, 0, v59, vcc
	v_cmp_ge_u32_e32 vcc, v6, v58
	v_addc_co_u32_e32 v59, vcc, 0, v59, vcc
	v_cmp_ge_u32_e32 vcc, v9, v58
	v_addc_co_u32_e32 v59, vcc, 0, v59, vcc
	v_cmp_ge_u32_e32 vcc, v8, v58
	v_addc_co_u32_e32 v59, vcc, 0, v59, vcc
	v_cmp_ge_u32_e32 vcc, v11, v58
	v_addc_co_u32_e32 v59, vcc, 0, v59, vcc
	v_cmp_ge_u32_e32 vcc, v10, v58
	v_addc_co_u32_e32 v59, vcc, 0, v59, vcc
	v_cmp_ge_u32_e32 vcc, v13, v58
	v_addc_co_u32_e32 v59, vcc, 0, v59, vcc
	v_cmp_ge_u32_e32 vcc, v12, v58
	v_addc_co_u32_e32 v59, vcc, 0, v59, vcc
	v_cmp_ge_u32_e32 vcc, v15, v58
	v_addc_co_u32_e32 v59, vcc, 0, v59, vcc
	v_cmp_ge_u32_e32 vcc, v14, v58
	v_addc_co_u32_e32 v59, vcc, 0, v59, vcc
	v_cmp_ge_u32_e32 vcc, v17, v58
	v_addc_co_u32_e32 v59, vcc, 0, v59, vcc
	v_cmp_ge_u32_e32 vcc, v16, v58
	v_addc_co_u32_e32 v59, vcc, 0, v59, vcc
	v_cmp_ge_u32_e32 vcc, v19, v58
	v_addc_co_u32_e32 v59, vcc, 0, v59, vcc
	v_cmp_ge_u32_e32 vcc, v18, v58
	v_addc_co_u32_e32 v59, vcc, 0, v59, vcc
	v_cmp_ge_u32_e32 vcc, v21, v58
	v_addc_co_u32_e32 v59, vcc, 0, v59, vcc
	v_cmp_ge_u32_e32 vcc, v20, v58
	v_addc_co_u32_e32 v59, vcc, 0, v59, vcc
	v_cmp_ge_u32_e32 vcc, v23, v58
	v_addc_co_u32_e32 v59, vcc, 0, v59, vcc
	v_cmp_ge_u32_e32 vcc, v22, v58
	v_addc_co_u32_e32 v59, vcc, 0, v59, vcc
	v_cmp_ge_u32_e32 vcc, v25, v58
	v_addc_co_u32_e32 v59, vcc, 0, v59, vcc
	v_cmp_ge_u32_e32 vcc, v24, v58
	v_addc_co_u32_e32 v59, vcc, 0, v59, vcc
	v_cmp_ge_u32_e32 vcc, v27, v58
	v_addc_co_u32_e32 v59, vcc, 0, v59, vcc
	v_cmp_ge_u32_e32 vcc, v26, v58
	v_addc_co_u32_e32 v59, vcc, 0, v59, vcc
	v_cmp_ge_u32_e32 vcc, v29, v58
	v_addc_co_u32_e32 v59, vcc, 0, v59, vcc
	v_cmp_ge_u32_e32 vcc, v28, v58
	v_addc_co_u32_e32 v59, vcc, 0, v59, vcc
	v_cmp_ge_u32_e32 vcc, v31, v58
	v_addc_co_u32_e32 v59, vcc, 0, v59, vcc
	v_cmp_ge_u32_e32 vcc, v30, v58
	v_addc_co_u32_e32 v59, vcc, 0, v59, vcc
	s_nop 1
	v_add_u32_dpp v59, v59, v59 row_shr:1 row_mask:0xf bank_mask:0xf bound_ctrl:1
	s_nop 1
	v_add_u32_dpp v59, v59, v59 row_shr:2 row_mask:0xf bank_mask:0xf bound_ctrl:1
	s_nop 1
	v_add_u32_dpp v59, v59, v59 row_shr:4 row_mask:0xf bank_mask:0xf bound_ctrl:1
	s_nop 1
	v_add_u32_dpp v59, v59, v59 row_shr:8 row_mask:0xf bank_mask:0xf bound_ctrl:1
	s_nop 1
	v_add_u32_dpp v59, v59, v59 row_bcast:15 row_mask:0xa bank_mask:0xf
	s_nop 1
	v_add_u32_dpp v59, v59, v59 row_bcast:31 row_mask:0xc bank_mask:0xf
	s_nop 0
	v_readlane_b32 s0, v59, 63
	s_cmpk_gt_i32 s0, 0xff
	s_cselect_b64 vcc, -1, 0
	s_cmpk_eq_i32 s0, 0x100
	v_cndmask_b32_e32 v56, v56, v58, vcc
	s_cselect_b64 s[0:1], -1, 0
	v_subrev_co_u32_e32 v57, vcc, 1, v57
	s_or_b64 s[0:1], s[0:1], vcc
	s_andn2_b64 vcc, exec, s[0:1]
	s_cbranch_vccnz .LBB0_449
	v_mov_b32_e32 v57, v98
	v_cmp_gt_u32_e32 vcc, v1, v56
	v_addc_co_u32_e32 v57, vcc, 0, v57, vcc
	v_mov_b32_e32 v58, v98
	v_cmp_gt_u32_e32 vcc, v0, v56
	v_addc_co_u32_e32 v57, vcc, 0, v57, vcc
	s_movk_i32 s64, 0x800
	v_cmp_gt_u32_e32 vcc, v3, v56
	v_addc_co_u32_e32 v57, vcc, 0, v57, vcc
	v_cmp_gt_u32_e32 vcc, v2, v56
	v_addc_co_u32_e32 v57, vcc, 0, v57, vcc
	v_cmp_gt_u32_e32 vcc, v5, v56
	v_addc_co_u32_e32 v57, vcc, 0, v57, vcc
	v_cmp_gt_u32_e32 vcc, v4, v56
	v_addc_co_u32_e32 v57, vcc, 0, v57, vcc
	v_cmp_gt_u32_e32 vcc, v7, v56
	v_addc_co_u32_e32 v57, vcc, 0, v57, vcc
	v_cmp_eq_u32_e32 vcc, v1, v56
	v_addc_co_u32_e32 v58, vcc, 0, v58, vcc
	v_cmp_gt_u32_e32 vcc, v6, v56
	v_addc_co_u32_e32 v57, vcc, 0, v57, vcc
	v_cmp_eq_u32_e32 vcc, v0, v56
	v_addc_co_u32_e32 v58, vcc, 0, v58, vcc
	v_cmp_gt_u32_e32 vcc, v9, v56
	v_addc_co_u32_e32 v57, vcc, 0, v57, vcc
	v_cmp_eq_u32_e32 vcc, v3, v56
	v_addc_co_u32_e32 v58, vcc, 0, v58, vcc
	v_cmp_gt_u32_e32 vcc, v8, v56
	v_addc_co_u32_e32 v57, vcc, 0, v57, vcc
	v_cmp_eq_u32_e32 vcc, v2, v56
	v_addc_co_u32_e32 v58, vcc, 0, v58, vcc
	v_cmp_gt_u32_e32 vcc, v11, v56
	v_addc_co_u32_e32 v57, vcc, 0, v57, vcc
	v_cmp_eq_u32_e32 vcc, v5, v56
	v_addc_co_u32_e32 v58, vcc, 0, v58, vcc
	v_cmp_gt_u32_e32 vcc, v10, v56
	v_addc_co_u32_e32 v57, vcc, 0, v57, vcc
	v_cmp_eq_u32_e32 vcc, v4, v56
	v_addc_co_u32_e32 v58, vcc, 0, v58, vcc
	v_cmp_gt_u32_e32 vcc, v13, v56
	v_addc_co_u32_e32 v57, vcc, 0, v57, vcc
	v_cmp_eq_u32_e32 vcc, v7, v56
	v_addc_co_u32_e32 v58, vcc, 0, v58, vcc
	v_cmp_gt_u32_e32 vcc, v12, v56
	v_addc_co_u32_e32 v57, vcc, 0, v57, vcc
	v_cmp_eq_u32_e32 vcc, v6, v56
	v_addc_co_u32_e32 v58, vcc, 0, v58, vcc
	v_cmp_gt_u32_e32 vcc, v15, v56
	v_addc_co_u32_e32 v57, vcc, 0, v57, vcc
	v_cmp_eq_u32_e32 vcc, v9, v56
	v_addc_co_u32_e32 v58, vcc, 0, v58, vcc
	v_cmp_gt_u32_e32 vcc, v14, v56
	v_addc_co_u32_e32 v57, vcc, 0, v57, vcc
	v_cmp_eq_u32_e32 vcc, v8, v56
;     ...
;     unsigned cg = 0u, ce = 0u;
; #pragma unroll
;     for (int j = 0; j < NJ; ++j) { asm("v_cmp_gt_u32_e32 vcc, %1, %2\n\tv_addc_co_u32_e32 %0, vcc, 0, %0, vcc" : "+v"(cg) : "v"(key[j]), "v"(T) : "vcc");
;                                    asm("v_cmp_eq_u32_e32 vcc, %1, %2\n\tv_addc_co_u32_e32 %0, vcc, 0, %0, vcc" : "+v"(ce) : "v"(key[j]), "v"(T) : "vcc"); }
;     const int gt = wave_count6(cg), eq = wave_count6(ce);
;     const int need = 256 - gt; int lim = SEQ;
;     if (eq > need) {
;         int X = 0;
; #pragma unroll 1
;     ...
; #pragma unroll
;             for (int j = 0; j < NJ; ++j) f += (key[j] == T && lane < c - 64 * j) ? 1u : 0u;
;             if (wave_count6(f) < need) X = c; }
;         lim = X + 1;
	v_addc_co_u32_e32 v58, vcc, 0, v58, vcc
	v_cmp_gt_u32_e32 vcc, v17, v56
	v_addc_co_u32_e32 v57, vcc, 0, v57, vcc
	v_cmp_eq_u32_e32 vcc, v11, v56
	v_addc_co_u32_e32 v58, vcc, 0, v58, vcc
	v_cmp_gt_u32_e32 vcc, v16, v56
	v_addc_co_u32_e32 v57, vcc, 0, v57, vcc
	v_cmp_eq_u32_e32 vcc, v10, v56
	v_addc_co_u32_e32 v58, vcc, 0, v58, vcc
	v_cmp_gt_u32_e32 vcc, v19, v56
	v_addc_co_u32_e32 v57, vcc, 0, v57, vcc
	v_cmp_eq_u32_e32 vcc, v13, v56
	v_addc_co_u32_e32 v58, vcc, 0, v58, vcc
	v_cmp_gt_u32_e32 vcc, v18, v56
	v_addc_co_u32_e32 v57, vcc, 0, v57, vcc
	v_cmp_eq_u32_e32 vcc, v12, v56
	v_addc_co_u32_e32 v58, vcc, 0, v58, vcc
	v_cmp_gt_u32_e32 vcc, v21, v56
	v_addc_co_u32_e32 v57, vcc, 0, v57, vcc
	v_cmp_eq_u32_e32 vcc, v15, v56
	v_addc_co_u32_e32 v58, vcc, 0, v58, vcc
	v_cmp_gt_u32_e32 vcc, v20, v56
	v_addc_co_u32_e32 v57, vcc, 0, v57, vcc
	v_cmp_eq_u32_e32 vcc, v14, v56
	v_addc_co_u32_e32 v58, vcc, 0, v58, vcc
	v_cmp_gt_u32_e32 vcc, v23, v56
	v_addc_co_u32_e32 v57, vcc, 0, v57, vcc
	v_cmp_eq_u32_e32 vcc, v17, v56
	v_addc_co_u32_e32 v58, vcc, 0, v58, vcc
	v_cmp_gt_u32_e32 vcc, v22, v56
	v_addc_co_u32_e32 v57, vcc, 0, v57, vcc
	v_cmp_eq_u32_e32 vcc, v16, v56
	v_addc_co_u32_e32 v58, vcc, 0, v58, vcc
	v_cmp_gt_u32_e32 vcc, v25, v56
	v_addc_co_u32_e32 v57, vcc, 0, v57, vcc
	v_cmp_eq_u32_e32 vcc, v19, v56
	v_addc_co_u32_e32 v58, vcc, 0, v58, vcc
	v_cmp_gt_u32_e32 vcc, v24, v56
	v_addc_co_u32_e32 v57, vcc, 0, v57, vcc
	v_cmp_eq_u32_e32 vcc, v18, v56
	v_addc_co_u32_e32 v58, vcc, 0, v58, vcc
	v_cmp_gt_u32_e32 vcc, v27, v56
	v_addc_co_u32_e32 v57, vcc, 0, v57, vcc
	v_cmp_eq_u32_e32 vcc, v21, v56
	v_addc_co_u32_e32 v58, vcc, 0, v58, vcc
	v_cmp_gt_u32_e32 vcc, v26, v56
	v_addc_co_u32_e32 v57, vcc, 0, v57, vcc
	v_cmp_eq_u32_e32 vcc, v20, v56
	v_addc_co_u32_e32 v58, vcc, 0, v58, vcc
	v_cmp_gt_u32_e32 vcc, v29, v56
	v_addc_co_u32_e32 v57, vcc, 0, v57, vcc
	v_cmp_eq_u32_e32 vcc, v23, v56
	v_addc_co_u32_e32 v58, vcc, 0, v58, vcc
	v_cmp_gt_u32_e32 vcc, v28, v56
	v_addc_co_u32_e32 v57, vcc, 0, v57, vcc
	v_cmp_eq_u32_e32 vcc, v22, v56
	v_addc_co_u32_e32 v58, vcc, 0, v58, vcc
	v_cmp_gt_u32_e32 vcc, v31, v56
	v_addc_co_u32_e32 v57, vcc, 0, v57, vcc
	v_cmp_eq_u32_e32 vcc, v25, v56
	v_addc_co_u32_e32 v58, vcc, 0, v58, vcc
	v_cmp_gt_u32_e32 vcc, v30, v56
	v_addc_co_u32_e32 v57, vcc, 0, v57, vcc
	v_cmp_eq_u32_e32 vcc, v24, v56
	v_addc_co_u32_e32 v58, vcc, 0, v58, vcc
	s_nop 0
	v_add_u32_dpp v57, v57, v57 row_shr:1 row_mask:0xf bank_mask:0xf bound_ctrl:1
	v_cmp_eq_u32_e32 vcc, v27, v56
	v_addc_co_u32_e32 v58, vcc, 0, v58, vcc
	v_cmp_eq_u32_e32 vcc, v26, v56
	v_addc_co_u32_e32 v58, vcc, 0, v58, vcc
	s_nop 0
	v_add_u32_dpp v57, v57, v57 row_shr:2 row_mask:0xf bank_mask:0xf bound_ctrl:1
	v_cmp_eq_u32_e32 vcc, v29, v56
	v_addc_co_u32_e32 v58, vcc, 0, v58, vcc
	v_cmp_eq_u32_e32 vcc, v28, v56
	v_addc_co_u32_e32 v58, vcc, 0, v58, vcc
	s_nop 0
	v_add_u32_dpp v57, v57, v57 row_shr:4 row_mask:0xf bank_mask:0xf bound_ctrl:1
	v_cmp_eq_u32_e32 vcc, v31, v56
	v_addc_co_u32_e32 v58, vcc, 0, v58, vcc
	v_cmp_eq_u32_e32 vcc, v30, v56
	v_addc_co_u32_e32 v58, vcc, 0, v58, vcc
	s_nop 0
	v_add_u32_dpp v57, v57, v57 row_shr:8 row_mask:0xf bank_mask:0xf bound_ctrl:1
	s_nop 1
	v_add_u32_dpp v57, v57, v57 row_bcast:15 row_mask:0xa bank_mask:0xf
	s_nop 1
	v_add_u32_dpp v57, v57, v57 row_bcast:31 row_mask:0xc bank_mask:0xf
	s_nop 0
	v_readlane_b32 s0, v57, 63
	v_add_u32_dpp v57, v58, v58 row_shr:1 row_mask:0xf bank_mask:0xf bound_ctrl:1
	s_sub_i32 s46, 0x100, s0
	s_nop 0
	v_add_u32_dpp v57, v57, v57 row_shr:2 row_mask:0xf bank_mask:0xf bound_ctrl:1
	s_nop 1
	v_add_u32_dpp v57, v57, v57 row_shr:4 row_mask:0xf bank_mask:0xf bound_ctrl:1
	s_nop 1
	v_add_u32_dpp v57, v57, v57 row_shr:8 row_mask:0xf bank_mask:0xf bound_ctrl:1
	s_nop 1
	v_add_u32_dpp v57, v57, v57 row_bcast:15 row_mask:0xa bank_mask:0xf
	s_nop 1
	v_add_u32_dpp v57, v57, v57 row_bcast:31 row_mask:0xc bank_mask:0xf
	s_nop 0
	v_readlane_b32 s1, v57, 63
	s_cmp_le_i32 s1, s46
	s_cbranch_scc1 .LBB0_454
	v_cmp_eq_u32_e64 s[4:5], v1, v56
	v_cmp_eq_u32_e64 s[76:77], v0, v56
	v_cmp_eq_u32_e64 s[78:79], v3, v56
	v_cmp_eq_u32_e64 s[80:81], v2, v56
	v_cmp_eq_u32_e64 s[82:83], v5, v56
	v_cmp_eq_u32_e64 s[84:85], v4, v56
	v_cmp_eq_u32_e64 s[86:87], v7, v56
	v_cmp_eq_u32_e64 s[88:89], v6, v56
	v_cmp_eq_u32_e64 s[90:91], v9, v56
	v_cmp_eq_u32_e64 s[92:93], v8, v56
	v_cmp_eq_u32_e64 s[94:95], v11, v56
	v_cmp_eq_u32_e64 s[96:97], v10, v56
	v_cmp_eq_u32_e64 s[6:7], v13, v56
	v_cmp_eq_u32_e64 s[10:11], v12, v56
	v_cmp_eq_u32_e64 s[0:1], v15, v56
	v_cmp_eq_u32_e64 s[12:13], v14, v56
	v_cmp_eq_u32_e64 s[14:15], v17, v56
	v_cmp_eq_u32_e64 s[16:17], v16, v56
	v_cmp_eq_u32_e64 s[18:19], v19, v56
	v_cmp_eq_u32_e64 s[20:21], v18, v56
	v_cmp_eq_u32_e64 s[22:23], v21, v56
	v_cmp_eq_u32_e64 s[74:75], v20, v56
	v_cmp_eq_u32_e64 s[24:25], v23, v56
	v_cmp_eq_u32_e64 s[26:27], v22, v56
	v_cmp_eq_u32_e64 s[28:29], v25, v56
	v_cmp_eq_u32_e64 s[30:31], v24, v56
	v_cmp_eq_u32_e64 s[34:35], v27, v56
	v_cmp_eq_u32_e64 s[36:37], v26, v56
	v_cmp_eq_u32_e64 s[38:39], v29, v56
	v_cmp_eq_u32_e64 s[40:41], v28, v56
	v_cmp_eq_u32_e64 s[42:43], v31, v56
	v_cmp_eq_u32_e64 s[44:45], v30, v56
	s_mov_b32 s47, 0
	s_mov_b32 s64, 10

;     ...
;     unsigned T = 0u;
; #pragma unroll 1
;     ...
;         const unsigned cand = T | (1u << bit);
;         unsigned c0 = 0u;
; #pragma unroll
;         for (int j = 0; j < NJ; ++j) asm("v_cmp_ge_u32_e32 vcc, %1, %2\n\tv_addc_co_u32_e32 %0, vcc, 0, %0, vcc" : "+v"(c0) : "v"(key[j]), "v"(cand) : "vcc");
;         const int cnt = wave_count6(c0);
;         if (cnt >= 256) T = cand;
;         if (cnt == 256) break;
;     }
.LBB0_459:
	v_lshlrev_b32_e64 v26, v25, 1
	v_mov_b32_e32 v27, 0
	v_or_b32_e32 v26, v26, v24
	v_cmp_ge_u32_e32 vcc, v1, v26
	v_addc_co_u32_e32 v27, vcc, 0, v27, vcc
	v_cmp_ge_u32_e32 vcc, v0, v26
	v_addc_co_u32_e32 v27, vcc, 0, v27, vcc
	v_cmp_ge_u32_e32 vcc, v3, v26
	v_addc_co_u32_e32 v27, vcc, 0, v27, vcc
	v_cmp_ge_u32_e32 vcc, v2, v26
	v_addc_co_u32_e32 v27, vcc, 0, v27, vcc
	v_cmp_ge_u32_e32 vcc, v5, v26
	v_addc_co_u32_e32 v27, vcc, 0, v27, vcc
	v_cmp_ge_u32_e32 vcc, v4, v26
	v_addc_co_u32_e32 v27, vcc, 0, v27, vcc
	v_cmp_ge_u32_e32 vcc, v7, v26
	v_addc_co_u32_e32 v27, vcc, 0, v27, vcc
	v_cmp_ge_u32_e32 vcc, v6, v26
	v_addc_co_u32_e32 v27, vcc, 0, v27, vcc
	v_cmp_ge_u32_e32 vcc, v9, v26
	v_addc_co_u32_e32 v27, vcc, 0, v27, vcc
	v_cmp_ge_u32_e32 vcc, v8, v26
	v_addc_co_u32_e32 v27, vcc, 0, v27, vcc
	v_cmp_ge_u32_e32 vcc, v11, v26
	v_addc_co_u32_e32 v27, vcc, 0, v27, vcc
	v_cmp_ge_u32_e32 vcc, v10, v26
	v_addc_co_u32_e32 v27, vcc, 0, v27, vcc
	v_cmp_ge_u32_e32 vcc, v13, v26
	v_addc_co_u32_e32 v27, vcc, 0, v27, vcc
	v_cmp_ge_u32_e32 vcc, v12, v26
	v_addc_co_u32_e32 v27, vcc, 0, v27, vcc
	v_cmp_ge_u32_e32 vcc, v15, v26
	v_addc_co_u32_e32 v27, vcc, 0, v27, vcc
	v_cmp_ge_u32_e32 vcc, v14, v26
	v_addc_co_u32_e32 v27, vcc, 0, v27, vcc
	v_cmp_ge_u32_e32 vcc, v17, v26
	v_addc_co_u32_e32 v27, vcc, 0, v27, vcc
	v_cmp_ge_u32_e32 vcc, v16, v26
	v_addc_co_u32_e32 v27, vcc, 0, v27, vcc
	v_cmp_ge_u32_e32 vcc, v19, v26
	v_addc_co_u32_e32 v27, vcc, 0, v27, vcc
	v_cmp_ge_u32_e32 vcc, v18, v26
	v_addc_co_u32_e32 v27, vcc, 0, v27, vcc
	v_cmp_ge_u32_e32 vcc, v21, v26
	v_addc_co_u32_e32 v27, vcc, 0, v27, vcc
	v_cmp_ge_u32_e32 vcc, v20, v26
	v_addc_co_u32_e32 v27, vcc, 0, v27, vcc
	v_cmp_ge_u32_e32 vcc, v23, v26
	v_addc_co_u32_e32 v27, vcc, 0, v27, vcc
	v_cmp_ge_u32_e32 vcc, v22, v26
	v_addc_co_u32_e32 v27, vcc, 0, v27, vcc
	s_nop 1
	v_add_u32_dpp v27, v27, v27 row_shr:1 row_mask:0xf bank_mask:0xf bound_ctrl:1
	s_nop 1
	v_add_u32_dpp v27, v27, v27 row_shr:2 row_mask:0xf bank_mask:0xf bound_ctrl:1
	s_nop 1
	v_add_u32_dpp v27, v27, v27 row_shr:4 row_mask:0xf bank_mask:0xf bound_ctrl:1
	s_nop 1
	v_add_u32_dpp v27, v27, v27 row_shr:8 row_mask:0xf bank_mask:0xf bound_ctrl:1
	s_nop 1
	v_add_u32_dpp v27, v27, v27 row_bcast:15 row_mask:0xa bank_mask:0xf
	s_nop 1
	v_add_u32_dpp v27, v27, v27 row_bcast:31 row_mask:0xc bank_mask:0xf
	s_nop 0
	v_readlane_b32 s0, v27, 63
	s_cmpk_gt_i32 s0, 0xff
	s_cselect_b64 vcc, -1, 0
	s_cmpk_eq_i32 s0, 0x100
	v_cndmask_b32_e32 v24, v24, v26, vcc
	s_cselect_b64 s[0:1], -1, 0
	v_subrev_co_u32_e32 v25, vcc, 1, v25
	s_or_b64 s[0:1], s[0:1], vcc
	s_andn2_b64 vcc, exec, s[0:1]
	s_cbranch_vccnz .LBB0_459
;     ...
;     unsigned cg = 0u, ce = 0u;
; #pragma unroll
;     for (int j = 0; j < NJ; ++j) { asm("v_cmp_gt_u32_e32 vcc, %1, %2\n\tv_addc_co_u32_e32 %0, vcc, 0, %0, vcc" : "+v"(cg) : "v"(key[j]), "v"(T) : "vcc");
;                                    asm("v_cmp_eq_u32_e32 vcc, %1, %2\n\tv_addc_co_u32_e32 %0, vcc, 0, %0, vcc" : "+v"(ce) : "v"(key[j]), "v"(T) : "vcc"); }
;     const int gt = wave_count6(cg), eq = wave_count6(ce);
;     const int need = 256 - gt; int lim = SEQ;
;     if (eq > need) {
;         int X = 0;
; #pragma unroll 1
;     ...
; #pragma unroll
;             for (int j = 0; j < NJ; ++j) f += (key[j] == T && lane < c - 64 * j) ? 1u : 0u;
;             if (wave_count6(f) < need) X = c; }
;         lim = X + 1;
	v_mov_b32_e32 v25, v98
	v_cmp_gt_u32_e32 vcc, v1, v24
	v_addc_co_u32_e32 v25, vcc, 0, v25, vcc
	v_mov_b32_e32 v26, v98
	v_cmp_gt_u32_e32 vcc, v0, v24
	v_addc_co_u32_e32 v25, vcc, 0, v25, vcc
	s_movk_i32 s45, 0x800
	v_cmp_gt_u32_e32 vcc, v3, v24
	v_addc_co_u32_e32 v25, vcc, 0, v25, vcc
	v_cmp_gt_u32_e32 vcc, v2, v24
	v_addc_co_u32_e32 v25, vcc, 0, v25, vcc
	v_cmp_gt_u32_e32 vcc, v5, v24
	v_addc_co_u32_e32 v25, vcc, 0, v25, vcc
	v_cmp_gt_u32_e32 vcc, v4, v24
	v_addc_co_u32_e32 v25, vcc, 0, v25, vcc
	v_cmp_gt_u32_e32 vcc, v7, v24
	v_addc_co_u32_e32 v25, vcc, 0, v25, vcc
	v_cmp_eq_u32_e32 vcc, v1, v24
	v_addc_co_u32_e32 v26, vcc, 0, v26, vcc
	v_cmp_gt_u32_e32 vcc, v6, v24
	v_addc_co_u32_e32 v25, vcc, 0, v25, vcc
	v_cmp_eq_u32_e32 vcc, v0, v24
	v_addc_co_u32_e32 v26, vcc, 0, v26, vcc
	v_cmp_gt_u32_e32 vcc, v9, v24
	v_addc_co_u32_e32 v25, vcc, 0, v25, vcc
	v_cmp_eq_u32_e32 vcc, v3, v24
	v_addc_co_u32_e32 v26, vcc, 0, v26, vcc
	v_cmp_gt_u32_e32 vcc, v8, v24
	v_addc_co_u32_e32 v25, vcc, 0, v25, vcc
	v_cmp_eq_u32_e32 vcc, v2, v24
	v_addc_co_u32_e32 v26, vcc, 0, v26, vcc
	v_cmp_gt_u32_e32 vcc, v11, v24
	v_addc_co_u32_e32 v25, vcc, 0, v25, vcc
	v_cmp_eq_u32_e32 vcc, v5, v24
	v_addc_co_u32_e32 v26, vcc, 0, v26, vcc
	v_cmp_gt_u32_e32 vcc, v10, v24
	v_addc_co_u32_e32 v25, vcc, 0, v25, vcc
	v_cmp_eq_u32_e32 vcc, v4, v24
	v_addc_co_u32_e32 v26, vcc, 0, v26, vcc
	v_cmp_gt_u32_e32 vcc, v13, v24
	v_addc_co_u32_e32 v25, vcc, 0, v25, vcc
	v_cmp_eq_u32_e32 vcc, v7, v24
	v_addc_co_u32_e32 v26, vcc, 0, v26, vcc
	v_cmp_gt_u32_e32 vcc, v12, v24
	v_addc_co_u32_e32 v25, vcc, 0, v25, vcc
	v_cmp_eq_u32_e32 vcc, v6, v24
	v_addc_co_u32_e32 v26, vcc, 0, v26, vcc
	v_cmp_gt_u32_e32 vcc, v15, v24
	v_addc_co_u32_e32 v25, vcc, 0, v25, vcc
	v_cmp_eq_u32_e32 vcc, v9, v24
	v_addc_co_u32_e32 v26, vcc, 0, v26, vcc
	v_cmp_gt_u32_e32 vcc, v14, v24
	v_addc_co_u32_e32 v25, vcc, 0, v25, vcc
	v_cmp_eq_u32_e32 vcc, v8, v24
	v_addc_co_u32_e32 v26, vcc, 0, v26, vcc
	v_cmp_gt_u32_e32 vcc, v17, v24
	v_addc_co_u32_e32 v25, vcc, 0, v25, vcc
	v_cmp_eq_u32_e32 vcc, v11, v24
	v_addc_co_u32_e32 v26, vcc, 0, v26, vcc
	v_cmp_gt_u32_e32 vcc, v16, v24
	v_addc_co_u32_e32 v25, vcc, 0, v25, vcc
	v_cmp_eq_u32_e32 vcc, v10, v24
	v_addc_co_u32_e32 v26, vcc, 0, v26, vcc
	v_cmp_gt_u32_e32 vcc, v19, v24
	v_addc_co_u32_e32 v25, vcc, 0, v25, vcc
	v_cmp_eq_u32_e32 vcc, v13, v24
	v_addc_co_u32_e32 v26, vcc, 0, v26, vcc
	v_cmp_gt_u32_e32 vcc, v18, v24
	v_addc_co_u32_e32 v25, vcc, 0, v25, vcc
	v_cmp_eq_u32_e32 vcc, v12, v24
	v_addc_co_u32_e32 v26, vcc, 0, v26, vcc
	v_cmp_gt_u32_e32 vcc, v21, v24
	v_addc_co_u32_e32 v25, vcc, 0, v25, vcc
	v_cmp_eq_u32_e32 vcc, v15, v24
	v_addc_co_u32_e32 v26, vcc, 0, v26, vcc
	v_cmp_gt_u32_e32 vcc, v20, v24
	v_addc_co_u32_e32 v25, vcc, 0, v25, vcc
	v_cmp_eq_u32_e32 vcc, v14, v24
	v_addc_co_u32_e32 v26, vcc, 0, v26, vcc
	v_cmp_gt_u32_e32 vcc, v23, v24
	v_addc_co_u32_e32 v25, vcc, 0, v25, vcc
	v_cmp_eq_u32_e32 vcc, v17, v24
	v_addc_co_u32_e32 v26, vcc, 0, v26, vcc
	v_cmp_gt_u32_e32 vcc, v22, v24
	v_addc_co_u32_e32 v25, vcc, 0, v25, vcc
	v_cmp_eq_u32_e32 vcc, v16, v24
	v_addc_co_u32_e32 v26, vcc, 0, v26, vcc
	s_nop 0
	v_add_u32_dpp v25, v25, v25 row_shr:1 row_mask:0xf bank_mask:0xf bound_ctrl:1
	v_cmp_eq_u32_e32 vcc, v19, v24
	v_addc_co_u32_e32 v26, vcc, 0, v26, vcc
	v_cmp_eq_u32_e32 vcc, v18, v24
	v_addc_co_u32_e32 v26, vcc, 0, v26, vcc
	s_nop 0
	v_add_u32_dpp v25, v25, v25 row_shr:2 row_mask:0xf bank_mask:0xf bound_ctrl:1
	v_cmp_eq_u32_e32 vcc, v21, v24
	v_addc_co_u32_e32 v26, vcc, 0, v26, vcc
	v_cmp_eq_u32_e32 vcc, v20, v24
	v_addc_co_u32_e32 v26, vcc, 0, v26, vcc
	s_nop 0
	v_add_u32_dpp v25, v25, v25 row_shr:4 row_mask:0xf bank_mask:0xf bound_ctrl:1
	v_cmp_eq_u32_e32 vcc, v23, v24
	v_addc_co_u32_e32 v26, vcc, 0, v26, vcc
	v_cmp_eq_u32_e32 vcc, v22, v24
	v_addc_co_u32_e32 v26, vcc, 0, v26, vcc
	s_nop 0
	v_add_u32_dpp v25, v25, v25 row_shr:8 row_mask:0xf bank_mask:0xf bound_ctrl:1
	s_nop 1
	v_add_u32_dpp v25, v25, v25 row_bcast:15 row_mask:0xa bank_mask:0xf
	s_nop 1
	v_add_u32_dpp v25, v25, v25 row_bcast:31 row_mask:0xc bank_mask:0xf
	s_nop 0
	v_readlane_b32 s0, v25, 63
	v_add_u32_dpp v25, v26, v26 row_shr:1 row_mask:0xf bank_mask:0xf bound_ctrl:1
	s_sub_i32 s44, 0x100, s0
	s_nop 0
	v_add_u32_dpp v25, v25, v25 row_shr:2 row_mask:0xf bank_mask:0xf bound_ctrl:1
	s_nop 1
	v_add_u32_dpp v25, v25, v25 row_shr:4 row_mask:0xf bank_mask:0xf bound_ctrl:1
	s_nop 1
	v_add_u32_dpp v25, v25, v25 row_shr:8 row_mask:0xf bank_mask:0xf bound_ctrl:1
	s_nop 1
	v_add_u32_dpp v25, v25, v25 row_bcast:15 row_mask:0xa bank_mask:0xf
	s_nop 1
	v_add_u32_dpp v25, v25, v25 row_bcast:31 row_mask:0xc bank_mask:0xf
	s_nop 0
	v_readlane_b32 s1, v25, 63
	s_cmp_le_i32 s1, s44
	s_cbranch_scc1 .LBB0_464
	v_cmp_eq_u32_e32 vcc, v1, v24
	v_cmp_eq_u32_e64 s[0:1], v0, v24
	v_cmp_eq_u32_e64 s[4:5], v3, v24
	v_cmp_eq_u32_e64 s[6:7], v2, v24
	v_cmp_eq_u32_e64 s[10:11], v5, v24
	v_cmp_eq_u32_e64 s[12:13], v4, v24
	v_cmp_eq_u32_e64 s[14:15], v7, v24
	v_cmp_eq_u32_e64 s[16:17], v6, v24
	v_cmp_eq_u32_e64 s[18:19], v9, v24
	v_cmp_eq_u32_e64 s[20:21], v8, v24
	v_cmp_eq_u32_e64 s[22:23], v11, v24
	v_cmp_eq_u32_e64 s[24:25], v10, v24
	v_cmp_eq_u32_e64 s[26:27], v13, v24
	v_cmp_eq_u32_e64 s[28:29], v12, v24
	v_cmp_eq_u32_e64 s[30:31], v15, v24
	v_cmp_eq_u32_e64 s[34:35], v14, v24
	v_cmp_eq_u32_e64 s[36:37], v17, v24
	v_cmp_eq_u32_e64 s[38:39], v16, v24
	v_cmp_eq_u32_e64 s[40:41], v19, v24
	v_cmp_eq_u32_e64 s[42:43], v18, v24
	v_cmp_eq_u32_e64 s[74:75], v21, v24
	v_cmp_eq_u32_e64 s[76:77], v20, v24
	v_cmp_eq_u32_e64 s[78:79], v23, v24
	v_cmp_eq_u32_e64 s[80:81], v22, v24
	s_mov_b32 s45, 0
	s_mov_b32 s46, 10

;     ...
;     unsigned T = 0u;
; #pragma unroll 1
;     ...
;         const unsigned cand = T | (1u << bit);
;         unsigned c0 = 0u;
; #pragma unroll
;         for (int j = 0; j < NJ; ++j) asm("v_cmp_ge_u32_e32 vcc, %1, %2\n\tv_addc_co_u32_e32 %0, vcc, 0, %0, vcc" : "+v"(c0) : "v"(key[j]), "v"(cand) : "vcc");
;         const int cnt = wave_count6(c0);
;         if (cnt >= 256) T = cand;
;         if (cnt == 256) break;
;     }
;     unsigned cg = 0u, ce = 0u;
; #pragma unroll
;     for (int j = 0; j < NJ; ++j) { asm("v_cmp_gt_u32_e32 vcc, %1, %2\n\tv_addc_co_u32_e32 %0, vcc, 0, %0, vcc" : "+v"(cg) : "v"(key[j]), "v"(T) : "vcc");
;                                    asm("v_cmp_eq_u32_e32 vcc, %1, %2\n\tv_addc_co_u32_e32 %0, vcc, 0, %0, vcc" : "+v"(ce) : "v"(key[j]), "v"(T) : "vcc"); }
;     const int gt = wave_count6(cg), eq = wave_count6(ce);
;     const int need = 256 - gt; int lim = SEQ;
;     if (eq > need) {
;         int X = 0;
; #pragma unroll 1
;     ...
; #pragma unroll
;             for (int j = 0; j < NJ; ++j) f += (key[j] == T && lane < c - 64 * j) ? 1u : 0u;
;             if (wave_count6(f) < need) X = c; }
;         lim = X + 1;
.LBB0_470:
	v_lshlrev_b32_e64 v18, v17, 1
	v_mov_b32_e32 v19, 0
	v_or_b32_e32 v18, v18, v16
	v_cmp_ge_u32_e32 vcc, v1, v18
	v_addc_co_u32_e32 v19, vcc, 0, v19, vcc
	v_cmp_ge_u32_e32 vcc, v0, v18
	v_addc_co_u32_e32 v19, vcc, 0, v19, vcc
	v_cmp_ge_u32_e32 vcc, v3, v18
	v_addc_co_u32_e32 v19, vcc, 0, v19, vcc
	v_cmp_ge_u32_e32 vcc, v2, v18
	v_addc_co_u32_e32 v19, vcc, 0, v19, vcc
	v_cmp_ge_u32_e32 vcc, v5, v18
	v_addc_co_u32_e32 v19, vcc, 0, v19, vcc
	v_cmp_ge_u32_e32 vcc, v4, v18
	v_addc_co_u32_e32 v19, vcc, 0, v19, vcc
	v_cmp_ge_u32_e32 vcc, v7, v18
	v_addc_co_u32_e32 v19, vcc, 0, v19, vcc
	v_cmp_ge_u32_e32 vcc, v6, v18
	v_addc_co_u32_e32 v19, vcc, 0, v19, vcc
	v_cmp_ge_u32_e32 vcc, v9, v18
	v_addc_co_u32_e32 v19, vcc, 0, v19, vcc
	v_cmp_ge_u32_e32 vcc, v8, v18
	v_addc_co_u32_e32 v19, vcc, 0, v19, vcc
	v_cmp_ge_u32_e32 vcc, v11, v18
	v_addc_co_u32_e32 v19, vcc, 0, v19, vcc
	v_cmp_ge_u32_e32 vcc, v10, v18
	v_addc_co_u32_e32 v19, vcc, 0, v19, vcc
	v_cmp_ge_u32_e32 vcc, v13, v18
	v_addc_co_u32_e32 v19, vcc, 0, v19, vcc
	v_cmp_ge_u32_e32 vcc, v12, v18
	v_addc_co_u32_e32 v19, vcc, 0, v19, vcc
	v_cmp_ge_u32_e32 vcc, v15, v18
	v_addc_co_u32_e32 v19, vcc, 0, v19, vcc
	v_cmp_ge_u32_e32 vcc, v14, v18
	v_addc_co_u32_e32 v19, vcc, 0, v19, vcc
	s_nop 1
	v_add_u32_dpp v19, v19, v19 row_shr:1 row_mask:0xf bank_mask:0xf bound_ctrl:1
	s_nop 1
	v_add_u32_dpp v19, v19, v19 row_shr:2 row_mask:0xf bank_mask:0xf bound_ctrl:1
	s_nop 1
	v_add_u32_dpp v19, v19, v19 row_shr:4 row_mask:0xf bank_mask:0xf bound_ctrl:1
	s_nop 1
	v_add_u32_dpp v19, v19, v19 row_shr:8 row_mask:0xf bank_mask:0xf bound_ctrl:1
	s_nop 1
	v_add_u32_dpp v19, v19, v19 row_bcast:15 row_mask:0xa bank_mask:0xf
	s_nop 1
	v_add_u32_dpp v19, v19, v19 row_bcast:31 row_mask:0xc bank_mask:0xf
	s_nop 0
	v_readlane_b32 s0, v19, 63
	s_cmpk_gt_i32 s0, 0xff
	s_cselect_b64 vcc, -1, 0
	s_cmpk_eq_i32 s0, 0x100
	v_cndmask_b32_e32 v16, v16, v18, vcc
	s_cselect_b64 s[0:1], -1, 0
	v_subrev_co_u32_e32 v17, vcc, 1, v17
	s_or_b64 s[0:1], s[0:1], vcc
	s_andn2_b64 vcc, exec, s[0:1]
	s_cbranch_vccnz .LBB0_470
	v_mov_b32_e32 v17, v98
	v_cmp_gt_u32_e32 vcc, v1, v16
	v_addc_co_u32_e32 v17, vcc, 0, v17, vcc
	v_mov_b32_e32 v18, v98
	v_cmp_gt_u32_e32 vcc, v0, v16
	v_addc_co_u32_e32 v17, vcc, 0, v17, vcc
	s_movk_i32 s40, 0x800
	v_cmp_gt_u32_e32 vcc, v3, v16
	v_addc_co_u32_e32 v17, vcc, 0, v17, vcc
	v_cmp_gt_u32_e32 vcc, v2, v16
	v_addc_co_u32_e32 v17, vcc, 0, v17, vcc
	v_cmp_gt_u32_e32 vcc, v5, v16
	v_addc_co_u32_e32 v17, vcc, 0, v17, vcc
	v_cmp_gt_u32_e32 vcc, v4, v16
	v_addc_co_u32_e32 v17, vcc, 0, v17, vcc
	v_cmp_gt_u32_e32 vcc, v7, v16
	v_addc_co_u32_e32 v17, vcc, 0, v17, vcc
	v_cmp_eq_u32_e32 vcc, v1, v16
	v_addc_co_u32_e32 v18, vcc, 0, v18, vcc
	v_cmp_gt_u32_e32 vcc, v6, v16
	v_addc_co_u32_e32 v17, vcc, 0, v17, vcc
	v_cmp_eq_u32_e32 vcc, v0, v16
	v_addc_co_u32_e32 v18, vcc, 0, v18, vcc
	v_cmp_gt_u32_e32 vcc, v9, v16
	v_addc_co_u32_e32 v17, vcc, 0, v17, vcc
	v_cmp_eq_u32_e32 vcc, v3, v16
	v_addc_co_u32_e32 v18, vcc, 0, v18, vcc
	v_cmp_gt_u32_e32 vcc, v8, v16
	v_addc_co_u32_e32 v17, vcc, 0, v17, vcc
	v_cmp_eq_u32_e32 vcc, v2, v16
	v_addc_co_u32_e32 v18, vcc, 0, v18, vcc
	v_cmp_gt_u32_e32 vcc, v11, v16
	v_addc_co_u32_e32 v17, vcc, 0, v17, vcc
	v_cmp_eq_u32_e32 vcc, v5, v16
	v_addc_co_u32_e32 v18, vcc, 0, v18, vcc
	v_cmp_gt_u32_e32 vcc, v10, v16
	v_addc_co_u32_e32 v17, vcc, 0, v17, vcc
	v_cmp_eq_u32_e32 vcc, v4, v16
	v_addc_co_u32_e32 v18, vcc, 0, v18, vcc
	v_cmp_gt_u32_e32 vcc, v13, v16
	v_addc_co_u32_e32 v17, vcc, 0, v17, vcc
	v_cmp_eq_u32_e32 vcc, v7, v16
	v_addc_co_u32_e32 v18, vcc, 0, v18, vcc
	v_cmp_gt_u32_e32 vcc, v12, v16
	v_addc_co_u32_e32 v17, vcc, 0, v17, vcc
	v_cmp_eq_u32_e32 vcc, v6, v16
	v_addc_co_u32_e32 v18, vcc, 0, v18, vcc
	v_cmp_gt_u32_e32 vcc, v15, v16
	v_addc_co_u32_e32 v17, vcc, 0, v17, vcc
	v_cmp_eq_u32_e32 vcc, v9, v16
	v_addc_co_u32_e32 v18, vcc, 0, v18, vcc
	v_cmp_gt_u32_e32 vcc, v14, v16
	v_addc_co_u32_e32 v17, vcc, 0, v17, vcc
	v_cmp_eq_u32_e32 vcc, v8, v16
	v_addc_co_u32_e32 v18, vcc, 0, v18, vcc
	s_nop 0
	v_add_u32_dpp v17, v17, v17 row_shr:1 row_mask:0xf bank_mask:0xf bound_ctrl:1
	v_cmp_eq_u32_e32 vcc, v11, v16
	v_addc_co_u32_e32 v18, vcc, 0, v18, vcc
	v_cmp_eq_u32_e32 vcc, v10, v16
	v_addc_co_u32_e32 v18, vcc, 0, v18, vcc
	s_nop 0
	v_add_u32_dpp v17, v17, v17 row_shr:2 row_mask:0xf bank_mask:0xf bound_ctrl:1
	v_cmp_eq_u32_e32 vcc, v13, v16
	v_addc_co_u32_e32 v18, vcc, 0, v18, vcc
	v_cmp_eq_u32_e32 vcc, v12, v16
	v_addc_co_u32_e32 v18, vcc, 0, v18, vcc
	s_nop 0
	v_add_u32_dpp v17, v17, v17 row_shr:4 row_mask:0xf bank_mask:0xf bound_ctrl:1
	v_cmp_eq_u32_e32 vcc, v15, v16
	v_addc_co_u32_e32 v18, vcc, 0, v18, vcc
	v_cmp_eq_u32_e32 vcc, v14, v16
	v_addc_co_u32_e32 v18, vcc, 0, v18, vcc
	s_nop 0
	v_add_u32_dpp v17, v17, v17 row_shr:8 row_mask:0xf bank_mask:0xf bound_ctrl:1
	s_nop 1
	v_add_u32_dpp v17, v17, v17 row_bcast:15 row_mask:0xa bank_mask:0xf
	s_nop 1
	v_add_u32_dpp v17, v17, v17 row_bcast:31 row_mask:0xc bank_mask:0xf
	s_nop 0
	v_readlane_b32 s0, v17, 63
	v_add_u32_dpp v17, v18, v18 row_shr:1 row_mask:0xf bank_mask:0xf bound_ctrl:1
	s_sub_i32 s38, 0x100, s0
	s_nop 0
	v_add_u32_dpp v17, v17, v17 row_shr:2 row_mask:0xf bank_mask:0xf bound_ctrl:1
	s_nop 1
	v_add_u32_dpp v17, v17, v17 row_shr:4 row_mask:0xf bank_mask:0xf bound_ctrl:1
	s_nop 1
	v_add_u32_dpp v17, v17, v17 row_shr:8 row_mask:0xf bank_mask:0xf bound_ctrl:1
	s_nop 1
	v_add_u32_dpp v17, v17, v17 row_bcast:15 row_mask:0xa bank_mask:0xf
	s_nop 1
	v_add_u32_dpp v17, v17, v17 row_bcast:31 row_mask:0xc bank_mask:0xf
	s_nop 0
	v_readlane_b32 s1, v17, 63
	s_cmp_le_i32 s1, s38
	s_cbranch_scc1 .LBB0_475
	v_cmp_eq_u32_e32 vcc, v1, v16
	v_cmp_eq_u32_e64 s[0:1], v0, v16
	v_cmp_eq_u32_e64 s[4:5], v3, v16
	v_cmp_eq_u32_e64 s[6:7], v2, v16
	v_cmp_eq_u32_e64 s[10:11], v5, v16
	v_cmp_eq_u32_e64 s[12:13], v4, v16
	v_cmp_eq_u32_e64 s[14:15], v7, v16
	v_cmp_eq_u32_e64 s[16:17], v6, v16
	v_cmp_eq_u32_e64 s[18:19], v9, v16
	v_cmp_eq_u32_e64 s[20:21], v8, v16
	v_cmp_eq_u32_e64 s[22:23], v11, v16
	v_cmp_eq_u32_e64 s[24:25], v10, v16
	v_cmp_eq_u32_e64 s[26:27], v13, v16
	v_cmp_eq_u32_e64 s[28:29], v12, v16
	v_cmp_eq_u32_e64 s[30:31], v15, v16
	v_cmp_eq_u32_e64 s[34:35], v14, v16
	s_mov_b32 s39, 0
	s_mov_b32 s40, 10

;     ...
;     unsigned T = 0u;
; #pragma unroll 1
;     ...
;         const unsigned cand = T | (1u << bit);
;         unsigned c0 = 0u;
; #pragma unroll
;         for (int j = 0; j < NJ; ++j) asm("v_cmp_ge_u32_e32 vcc, %1, %2\n\tv_addc_co_u32_e32 %0, vcc, 0, %0, vcc" : "+v"(c0) : "v"(key[j]), "v"(cand) : "vcc");
;         const int cnt = wave_count6(c0);
;         if (cnt >= 256) T = cand;
;         if (cnt == 256) break;
;     }
;     unsigned cg = 0u, ce = 0u;
; #pragma unroll
;     for (int j = 0; j < NJ; ++j) { asm("v_cmp_gt_u32_e32 vcc, %1, %2\n\tv_addc_co_u32_e32 %0, vcc, 0, %0, vcc" : "+v"(cg) : "v"(key[j]), "v"(T) : "vcc");
;                                    asm("v_cmp_eq_u32_e32 vcc, %1, %2\n\tv_addc_co_u32_e32 %0, vcc, 0, %0, vcc" : "+v"(ce) : "v"(key[j]), "v"(T) : "vcc"); }
;     const int gt = wave_count6(cg), eq = wave_count6(ce);
;     const int need = 256 - gt; int lim = SEQ;
;     if (eq > need) {
;         int X = 0;
; #pragma unroll 1
;     ...
; #pragma unroll
;             for (int j = 0; j < NJ; ++j) f += (key[j] == T && lane < c - 64 * j) ? 1u : 0u;
;             if (wave_count6(f) < need) X = c; }
;         lim = X + 1;
.LBB0_480:
	v_lshlrev_b32_e64 v10, v9, 1
	v_mov_b32_e32 v11, 0
	v_or_b32_e32 v10, v10, v8
	v_cmp_ge_u32_e32 vcc, v1, v10
	v_addc_co_u32_e32 v11, vcc, 0, v11, vcc
	v_cmp_ge_u32_e32 vcc, v0, v10
	v_addc_co_u32_e32 v11, vcc, 0, v11, vcc
	v_cmp_ge_u32_e32 vcc, v3, v10
	v_addc_co_u32_e32 v11, vcc, 0, v11, vcc
	v_cmp_ge_u32_e32 vcc, v2, v10
	v_addc_co_u32_e32 v11, vcc, 0, v11, vcc
	v_cmp_ge_u32_e32 vcc, v5, v10
	v_addc_co_u32_e32 v11, vcc, 0, v11, vcc
	v_cmp_ge_u32_e32 vcc, v4, v10
	v_addc_co_u32_e32 v11, vcc, 0, v11, vcc
	v_cmp_ge_u32_e32 vcc, v7, v10
	v_addc_co_u32_e32 v11, vcc, 0, v11, vcc
	v_cmp_ge_u32_e32 vcc, v6, v10
	v_addc_co_u32_e32 v11, vcc, 0, v11, vcc
	s_nop 1
	v_add_u32_dpp v11, v11, v11 row_shr:1 row_mask:0xf bank_mask:0xf bound_ctrl:1
	s_nop 1
	v_add_u32_dpp v11, v11, v11 row_shr:2 row_mask:0xf bank_mask:0xf bound_ctrl:1
	s_nop 1
	v_add_u32_dpp v11, v11, v11 row_shr:4 row_mask:0xf bank_mask:0xf bound_ctrl:1
	s_nop 1
	v_add_u32_dpp v11, v11, v11 row_shr:8 row_mask:0xf bank_mask:0xf bound_ctrl:1
	s_nop 1
	v_add_u32_dpp v11, v11, v11 row_bcast:15 row_mask:0xa bank_mask:0xf
	s_nop 1
	v_add_u32_dpp v11, v11, v11 row_bcast:31 row_mask:0xc bank_mask:0xf
	s_nop 0
	v_readlane_b32 s0, v11, 63
	s_cmpk_gt_i32 s0, 0xff
	s_cselect_b64 vcc, -1, 0
	s_cmpk_eq_i32 s0, 0x100
	v_cndmask_b32_e32 v8, v8, v10, vcc
	s_cselect_b64 s[0:1], -1, 0
	v_subrev_co_u32_e32 v9, vcc, 1, v9
	s_or_b64 s[0:1], s[0:1], vcc
	s_andn2_b64 vcc, exec, s[0:1]
	s_cbranch_vccnz .LBB0_480
	v_mov_b32_e32 v9, v98
	v_cmp_gt_u32_e32 vcc, v1, v8
	v_addc_co_u32_e32 v9, vcc, 0, v9, vcc
	v_mov_b32_e32 v10, v98
	v_cmp_gt_u32_e32 vcc, v0, v8
	v_addc_co_u32_e32 v9, vcc, 0, v9, vcc
	s_movk_i32 s22, 0x800
	v_cmp_gt_u32_e32 vcc, v3, v8
	v_addc_co_u32_e32 v9, vcc, 0, v9, vcc
	v_cmp_gt_u32_e32 vcc, v2, v8
	v_addc_co_u32_e32 v9, vcc, 0, v9, vcc
	v_cmp_gt_u32_e32 vcc, v5, v8
	v_addc_co_u32_e32 v9, vcc, 0, v9, vcc
	v_cmp_gt_u32_e32 vcc, v4, v8
	v_addc_co_u32_e32 v9, vcc, 0, v9, vcc
	v_cmp_gt_u32_e32 vcc, v7, v8
	v_addc_co_u32_e32 v9, vcc, 0, v9, vcc
	v_cmp_eq_u32_e32 vcc, v1, v8
	v_addc_co_u32_e32 v10, vcc, 0, v10, vcc
	v_cmp_gt_u32_e32 vcc, v6, v8
	v_addc_co_u32_e32 v9, vcc, 0, v9, vcc
	v_cmp_eq_u32_e32 vcc, v0, v8
	v_addc_co_u32_e32 v10, vcc, 0, v10, vcc
	s_nop 0
	v_add_u32_dpp v9, v9, v9 row_shr:1 row_mask:0xf bank_mask:0xf bound_ctrl:1
	v_cmp_eq_u32_e32 vcc, v3, v8
	v_addc_co_u32_e32 v10, vcc, 0, v10, vcc
	v_cmp_eq_u32_e32 vcc, v2, v8
	v_addc_co_u32_e32 v10, vcc, 0, v10, vcc
	s_nop 0
	v_add_u32_dpp v9, v9, v9 row_shr:2 row_mask:0xf bank_mask:0xf bound_ctrl:1
	v_cmp_eq_u32_e32 vcc, v5, v8
	v_addc_co_u32_e32 v10, vcc, 0, v10, vcc
	v_cmp_eq_u32_e32 vcc, v4, v8
	v_addc_co_u32_e32 v10, vcc, 0, v10, vcc
	s_nop 0
	v_add_u32_dpp v9, v9, v9 row_shr:4 row_mask:0xf bank_mask:0xf bound_ctrl:1
	v_cmp_eq_u32_e32 vcc, v7, v8
	v_addc_co_u32_e32 v10, vcc, 0, v10, vcc
	v_cmp_eq_u32_e32 vcc, v6, v8
	v_addc_co_u32_e32 v10, vcc, 0, v10, vcc
	s_nop 0
	v_add_u32_dpp v9, v9, v9 row_shr:8 row_mask:0xf bank_mask:0xf bound_ctrl:1
	s_nop 1
	v_add_u32_dpp v9, v9, v9 row_bcast:15 row_mask:0xa bank_mask:0xf
	s_nop 1
	v_add_u32_dpp v9, v9, v9 row_bcast:31 row_mask:0xc bank_mask:0xf
	s_nop 0
	v_readlane_b32 s0, v9, 63
	v_add_u32_dpp v9, v10, v10 row_shr:1 row_mask:0xf bank_mask:0xf bound_ctrl:1
	s_sub_i32 s20, 0x100, s0
	s_nop 0
	v_add_u32_dpp v9, v9, v9 row_shr:2 row_mask:0xf bank_mask:0xf bound_ctrl:1
	s_nop 1
	v_add_u32_dpp v9, v9, v9 row_shr:4 row_mask:0xf bank_mask:0xf bound_ctrl:1
	s_nop 1
	v_add_u32_dpp v9, v9, v9 row_shr:8 row_mask:0xf bank_mask:0xf bound_ctrl:1
	s_nop 1
	v_add_u32_dpp v9, v9, v9 row_bcast:15 row_mask:0xa bank_mask:0xf
	s_nop 1
	v_add_u32_dpp v9, v9, v9 row_bcast:31 row_mask:0xc bank_mask:0xf
	s_nop 0
	v_readlane_b32 s1, v9, 63
	s_cmp_le_i32 s1, s20
	s_cbranch_scc1 .LBB0_485
	v_cmp_eq_u32_e32 vcc, v1, v8
	v_cmp_eq_u32_e64 s[0:1], v0, v8
	v_cmp_eq_u32_e64 s[4:5], v3, v8
	v_cmp_eq_u32_e64 s[6:7], v2, v8
	v_cmp_eq_u32_e64 s[10:11], v5, v8
	v_cmp_eq_u32_e64 s[12:13], v4, v8
	v_cmp_eq_u32_e64 s[14:15], v7, v8
	v_cmp_eq_u32_e64 s[16:17], v6, v8
	s_mov_b32 s21, 0
	s_mov_b32 s22, 10
